# attention work queue: next unit id fetched one unit ahead, handed over via ds_write/ds_read (one barrier, no flat ops)
# baseline (speedup 1.0000x reference)
.LBB0_786:
	s_andn2_b64 vcc, exec, s[4:5]
	s_cbranch_vccnz .LBB0_856
	v_readlane_b32 s4, v254, 0
	v_readlane_b32 s5, v254, 1
	s_load_dwordx4 s[36:39], s[4:5], 0xb8
	v_readlane_b32 s4, v253, 32
	v_readlane_b32 s5, v253, 33
	s_mov_b32 s7, s5
	v_readlane_b32 s4, v253, 36
	s_waitcnt lgkmcnt(0)
	s_add_u32 s62, s36, 0x3cb2000
	s_addc_u32 s63, s37, 0
	s_add_u32 s70, s38, 0x11139000
	s_addc_u32 s71, s39, 0
	s_add_u32 s88, s38, 0x131b9000
	s_addc_u32 s89, s39, 0
	s_add_u32 s54, s38, 0x8f21000
	s_addc_u32 s55, s39, 0
	v_readlane_b32 s5, v253, 37
	s_add_u32 s44, s38, 0xf0b1000
	s_mov_b32 s5, s7
	s_addc_u32 s45, s39, 0
	s_lshl_b32 s6, s4, 4
	v_writelane_b32 v253, s4, 32
	v_mov_b32_e32 v127, v192
	v_mov_b32_e32 v125, v173
	v_writelane_b32 v253, s5, 33
	s_lshl_b64 s[4:5], s[6:7], 2
	s_add_u32 s4, s38, s4
	v_ashrrev_i32_e32 v122, 3, v127
	s_addc_u32 s5, s39, s5
	v_max_i32_e32 v0, 48, v122
	v_writelane_b32 v253, s4, 38
	v_readfirstlane_b32 s0, v127
	v_subrev_u32_e32 v124, 48, v0
	v_lshlrev_b32_e32 v0, 3, v127
	v_and_b32_e32 v154, 63, v127
	v_writelane_b32 v253, s5, 39
	v_bfe_u32 v1, v127, 4, 2
	s_ashr_i32 s0, s0, 1
	v_and_b32_e32 v172, 48, v127
	v_and_b32_e32 v126, 56, v0
	s_movk_i32 s4, 0x48
	v_and_b32_e32 v155, 15, v127
	s_and_b32 s85, s0, 0xffffffe0
	v_lshlrev_b32_e32 v157, 3, v1
	v_lshl_add_u64 v[120:121], s[54:55], 0, v[172:173]
	v_max_u32_e32 v0, 48, v126
	v_max_u32_e32 v2, 48, v154
	v_mul_lo_u32 v3, v122, s4
	v_lshlrev_b32_e32 v158, 2, v1
	v_lshlrev_b32_e32 v1, 2, v154
	v_lshlrev_b32_e32 v172, 1, v126
	v_cmp_eq_u32_e32 vcc, 0, v127
	v_or_b32_e32 v156, s85, v155
	v_ashrrev_i32_e32 v123, 31, v122
	v_cmp_gt_i32_e64 s[4:5], 64, v127
	s_or_b32 s93, s0, 31
	v_mul_u32_u24_e32 v159, 0x48, v155
	v_xor_b32_e32 v160, 64, v1
	v_xor_b32_e32 v161, 0x80, v1
	v_lshl_add_u64 v[128:129], s[70:71], 0, v[172:173]
	v_sub_u32_e32 v162, 0, v157
	s_mov_b64 s[66:67], 0
	v_lshlrev_b32_e32 v130, 1, v0
	v_lshlrev_b32_e32 v132, 2, v2
	v_lshlrev_b32_e32 v163, 1, v3
	s_mov_b64 exec, vcc
	s_cbranch_execz .Lattn_q_skip0
	v_readlane_b32 s100, v253, 38
	v_readlane_b32 s101, v253, 39
	v_mov_b32_e32 v251, 1
	s_nop 3
	global_atomic_add v250, v173, v251, s[100:101] offset:64 sc0
.Lattn_q_skip0:
	s_mov_b64 exec, -1
	s_branch .LBB0_790

.LBB0_790:
	s_waitcnt vmcnt(0)
	s_and_saveexec_b64 s[8:9], vcc
	v_mov_b32_e32 v251, 0x9200
	ds_write_b32 v251, v250
	s_or_b64 exec, exec, s[8:9]
	s_waitcnt lgkmcnt(0)
	s_barrier
	v_mov_b32_e32 v0, 0x9200
	ds_read_b32 v0, v0
	s_movk_i32 s0, 0x480
	s_mov_b64 s[8:9], -1
	s_waitcnt lgkmcnt(0)
	v_cmp_gt_i32_e64 s[6:7], s0, v0
	s_and_saveexec_b64 s[68:69], s[6:7]
	s_cbranch_execz .LBB0_789
	s_mov_b64 exec, vcc
	s_cbranch_execz .Lattn_q_skip1
	v_readlane_b32 s100, v253, 38
	v_readlane_b32 s101, v253, 39
	v_mov_b32_e32 v251, 1
	s_nop 3
	global_atomic_add v250, v173, v251, s[100:101] offset:64 sc0
.Lattn_q_skip1:
	s_mov_b64 exec, -1
	v_ashrrev_i32_e32 v1, 31, v0
	v_lshrrev_b32_e32 v1, 25, v1
	v_add_u32_e32 v1, v0, v1
	v_ashrrev_i32_e32 v8, 7, v1
	v_and_b32_e32 v1, 0xffffff80, v1
	v_sub_u32_e32 v0, v0, v1
	v_mov_b32_e32 v1, 11
	v_lshrrev_b16_sdwa v1, v1, sext(v0) dst_sel:DWORD dst_unused:UNUSED_PAD src0_sel:DWORD src1_sel:BYTE_0
	v_and_b32_e32 v1, 15, v1
	v_add_u16_e32 v1, v0, v1
	v_sub_u32_e32 v9, 8, v8
	v_ashrrev_i16_sdwa v2, v198, sext(v1) dst_sel:DWORD dst_unused:UNUSED_PAD src0_sel:DWORD src1_sel:BYTE_0
	s_movk_i32 s0, 0x810
	v_and_b32_e32 v1, 0xf0, v1
	v_mul_hi_i32_i24_sdwa v135, sext(v2), s0 dst_sel:DWORD dst_unused:UNUSED_PAD src0_sel:WORD_0 src1_sel:DWORD
	v_mul_i32_i24_sdwa v134, sext(v2), s0 dst_sel:DWORD dst_unused:UNUSED_PAD src0_sel:WORD_0 src1_sel:DWORD
	v_mul_hi_i32_i24_e32 v3, 0x2040, v0
	v_mul_i32_i24_e32 v2, 0x2040, v0
	v_lshlrev_b32_e32 v10, 8, v9
	v_sub_u16_e32 v4, v0, v1
	v_lshl_add_u64 v[140:141], s[62:63], 0, v[2:3]
	v_add_u32_e32 v164, v10, v156
	v_mov_b32_e32 v2, 6
	v_lshlrev_b32_sdwa v138, v2, sext(v4) dst_sel:DWORD dst_unused:UNUSED_PAD src0_sel:DWORD src1_sel:BYTE_0
	v_max_i32_e32 v6, 0xf0, v164
	v_ashrrev_i32_e32 v139, 31, v138
	v_add_u32_e32 v172, 0xffffff10, v6
	v_lshlrev_b64 v[2:3], 1, v[138:139]
	v_lshl_add_u64 v[6:7], v[134:135], 0, v[172:173]
	v_lshl_add_u64 v[4:5], v[120:121], 0, v[2:3]
	v_lshlrev_b64 v[6:7], 12, v[6:7]
	v_lshl_add_u64 v[6:7], v[4:5], 0, v[6:7]
	v_or_b32_e32 v139, 16, v164
	global_load_dwordx4 v[20:23], v[6:7], off
	global_load_dwordx4 v[24:27], v[6:7], off offset:64
	v_max_i32_e32 v6, 0xf0, v139
	v_add_u32_e32 v172, 0xffffff10, v6
	v_lshl_add_u64 v[6:7], v[134:135], 0, v[172:173]
	v_lshlrev_b64 v[6:7], 12, v[6:7]
	v_ashrrev_i32_e32 v1, 31, v0
	v_lshl_add_u64 v[4:5], v[4:5], 0, v[6:7]
	global_load_dwordx4 v[28:31], v[4:5], off
	global_load_dwordx4 v[32:35], v[4:5], off offset:64
	v_lshl_add_u64 v[4:5], v[134:135], 0, v[124:125]
	v_lshlrev_b64 v[0:1], 6, v[0:1]
	v_lshlrev_b64 v[4:5], 11, v[4:5]
	v_lshl_add_u64 v[0:1], v[0:1], 0, v[122:123]
	v_mov_b64_e32 v[6:7], s[88:89]
	v_lshl_add_u64 v[4:5], s[70:71], 0, v[4:5]
	v_mad_u64_u32 v[144:145], s[6:7], v0, s52, v[6:7]
	v_lshl_add_u64 v[4:5], v[4:5], 0, v[2:3]
	v_lshlrev_b32_e32 v142, 1, v126
	v_mov_b32_e32 v143, v173
	v_mad_i32_i24 v145, v1, s52, v145
	v_mov_b32_e32 v131, v173
	v_lshlrev_b32_e32 v165, 2, v9
	v_lshl_add_u64 v[4:5], v[4:5], 0, v[142:143]
	v_lshl_add_u64 v[0:1], v[144:145], 0, v[130:131]
	v_mov_b32_e32 v133, v173
	v_or_b32_e32 v166, 3, v165
	global_load_dwordx4 v[36:39], v[4:5], off
	global_load_dwordx4 v[40:43], v[0:1], off offset:-96
	v_lshl_add_u64 v[0:1], v[140:141], 0, v[132:133]
	global_load_dword v131, v[0:1], off offset:-192
	v_min_u32_e32 v0, 4, v166
	v_lshl_add_u32 v6, v0, 6, v201
	v_add_u32_e32 v0, v6, v122
	v_max_i32_e32 v172, 0, v0
	v_lshl_add_u64 v[0:1], v[134:135], 0, v[172:173]
	v_lshlrev_b64 v[0:1], 11, v[0:1]
	v_lshl_add_u64 v[0:1], s[70:71], 0, v[0:1]
	v_add_u32_e32 v4, v6, v126
	v_lshl_add_u64 v[0:1], v[0:1], 0, v[2:3]
	v_max_i32_e32 v4, 0, v4
	v_lshl_add_u64 v[0:1], v[0:1], 0, v[142:143]
	v_lshlrev_b32_e32 v172, 1, v4
	v_lshl_add_u64 v[4:5], v[144:145], 0, v[172:173]
	global_load_dwordx4 v[44:47], v[0:1], off
	global_load_dwordx4 v[48:51], v[4:5], off
	v_add_u32_e32 v0, v6, v154
	v_max_i32_e32 v0, 0, v0
	v_lshlrev_b32_e32 v172, 2, v0
	v_lshl_add_u64 v[0:1], v[140:141], 0, v[172:173]
	global_load_dword v167, v[0:1], off
	v_min_u32_e32 v0, 5, v166
	v_lshl_add_u32 v6, v0, 6, v201
	v_add_u32_e32 v0, v6, v122
	v_max_i32_e32 v172, 0, v0
	v_lshl_add_u64 v[0:1], v[134:135], 0, v[172:173]
	v_lshlrev_b64 v[0:1], 11, v[0:1]
	v_lshl_add_u64 v[0:1], s[70:71], 0, v[0:1]
	v_add_u32_e32 v4, v6, v126
	v_lshl_add_u64 v[0:1], v[0:1], 0, v[2:3]
	v_max_i32_e32 v4, 0, v4
	v_lshl_add_u64 v[0:1], v[0:1], 0, v[142:143]
	v_lshlrev_b32_e32 v172, 1, v4
	v_lshl_add_u64 v[4:5], v[144:145], 0, v[172:173]
	global_load_dwordx4 v[52:55], v[0:1], off
	global_load_dwordx4 v[56:59], v[4:5], off
	v_add_u32_e32 v0, v6, v154
	v_max_i32_e32 v0, 0, v0
	v_lshlrev_b32_e32 v172, 2, v0
	v_lshl_add_u64 v[0:1], v[140:141], 0, v[172:173]
	global_load_dword v169, v[0:1], off
	v_sub_u32_e32 v0, 0, v8
	v_or_b32_e32 v1, v10, v155
	v_lshl_add_u64 v[146:147], v[128:129], 0, v[2:3]
	v_lshlrev_b32_e32 v0, 8, v0
	v_mov_b32_e32 v2, v173
	v_mov_b32_e32 v3, v173
	v_add_u32_e32 v133, s85, v1
	v_sub_u32_e32 v168, 0, v0
	v_mov_b32_e32 v172, v173
	v_mov_b32_e32 v0, v173
	v_mov_b32_e32 v1, v173
	v_mov_b64_e32 v[6:7], v[2:3]
	v_mov_b64_e32 v[10:11], v[2:3]
	v_mov_b64_e32 v[14:15], v[2:3]
	v_mov_b64_e32 v[18:19], v[2:3]
	v_mov_b64_e32 v[62:63], v[2:3]
	v_mov_b64_e32 v[66:67], v[2:3]
	v_mov_b64_e32 v[70:71], v[2:3]
	s_mov_b32 s60, s87
	s_mov_b32 s84, 0
	v_or_b32_e32 v143, 16, v133
	v_mov_b32_e32 v148, 0xff800000
	s_mov_b64 s[34:35], 0
	v_mov_b32_e32 v170, 0
	s_mov_b32 s87, 0
	v_mov_b64_e32 v[4:5], v[0:1]
	v_mov_b64_e32 v[8:9], v[0:1]
	v_mov_b64_e32 v[12:13], v[0:1]
	v_mov_b64_e32 v[16:17], v[0:1]
	v_mov_b64_e32 v[60:61], v[0:1]
	v_mov_b64_e32 v[64:65], v[0:1]
	v_mov_b64_e32 v[68:69], v[0:1]
	v_mov_b64_e32 v[136:137], v[172:173]
	v_mov_b32_e32 v149, 0xff800000
	s_branch .LBB0_798
